# GDN MFMA loop: loads issued one iteration ahead, Minv loaded directly, pads trimmed
# baseline (speedup 1.0000x reference)
; __device__ __forceinline__ int otid() { int t = threadIdx.x; asm volatile("" : "+v"(t)); return t; }
; __device__ __forceinline__ void gdn_item(const Params& p, int item, float* sm) {
;   const int b = item >> 5, h = (item >> 3) & 3, c0 = (item & 7) * 16;
;   const bf16_t* gp = (const bf16_t*)p.out;
;   const float* gg = (const float*)(p.ws + OFF_GG);
;   bf16_t* O = (bf16_t*)(p.ws + OFF_O);
;   constexpr int TC = 16;
;   constexpr int BUF = 2 * TC * 128 + TC * 16 + 2 * TC + TC * 16 + TC;
;   const int tid = otid(), lane = tid & 63, wave = tid >> 6;
;   const int sub = lane & 15, cw = wave * 4 + (lane >> 4);
;   const int ltt = tid >> 4, lseg = tid & 15;
;   float S[8];
; #pragma unroll
;   for (int i = 0; i < 8; i++) S[i] = 0.f;
;   const size_t rowb = (size_t)b * LP;
;   uint4 pq, pk; bf16_t pv; float pg = 0.f, pb = 0.f;
;     ...
;   __syncthreads();
;   GDN_LOAD(PADR)
;   GDN_STORE(0)
;   __syncthreads();
.Lgd_item:
	s_setprio 3
	v_readlane_b32 s14, v244, 27
	v_readlane_b32 s8, v247, 3
	v_readlane_b32 s9, v247, 4
	v_readlane_b32 s4, v247, 1
	v_readlane_b32 s5, v247, 2
	v_and_b32_e32 v136, 15, v2
	v_lshrrev_b32_e32 v137, 4, v2
	v_bfe_u32 v138, v2, 4, 2
	v_lshrrev_b32_e32 v139, 6, v2
	s_lshr_b32 s10, s14, 5
	s_bfe_u32 s11, s14, 0x20003
	s_and_b32 s12, s14, 7
	s_lshl_b32 s12, s12, 5
	s_mul_i32 s13, s10, 0x2080
	s_add_i32 s13, s13, 0x70
	s_add_u32 s6, s8, 0x19c8c000
	s_addc_u32 s7, s9, 0
	s_add_u32 s8, s8, 0x19d90000
	s_addc_u32 s9, s9, 0
	s_lshl_b32 s14, s10, 2
	s_add_i32 s14, s14, s11
	s_mul_i32 s14, s14, 0x80400
	s_add_u32 s10, s4, 0x71a0000
	s_addc_u32 s15, s5, 0
	s_add_u32 s10, s10, s14
	s_addc_u32 s11, s15, 0
	v_readfirstlane_b32 s100, v139
	v_lshlrev_b32_e32 v151, 9, v136
	v_lshl_add_u32 v151, v139, 7, v151
	v_lshl_add_u32 v151, v138, 4, v151
	v_lshlrev_b32_e32 v152, 11, v138
	v_lshl_add_u32 v152, v139, 7, v152
	v_lshl_add_u32 v152, v136, 2, v152
	v_lshlrev_b32_e32 v153, 6, v136
	v_lshl_add_u32 v153, v138, 4, v153
	v_lshlrev_b32_e32 v154, 4, v138
	v_and_b32_e32 v140, 63, v2
	v_lshlrev_b32_e32 v156, 4, v140
	v_add_u32_e32 v156, 0x8a00, v156
	s_mul_i32 s101, s100, 0xc00
	v_add_u32_e32 v155, s101, v156
	v_lshlrev_b32_e32 v157, 5, v2
	v_lshl_add_u32 v158, v136, 4, v137
	v_lshlrev_b32_e32 v158, 2, v158
	v_add_u32_e32 v158, 16384, v158
	v_lshlrev_b32_e32 v159, 2, v136
	v_lshlrev_b32_e32 v141, 2, v138
	v_add_u32_e32 v142, 0, v141
	v_cmp_le_u32_e32 vcc, v142, v136
	s_nop 1
	v_cndmask_b32_e64 v166, 0, 1.0, vcc
	v_add_u32_e32 v142, 1, v141
	v_cmp_le_u32_e32 vcc, v142, v136
	s_nop 1
	v_cndmask_b32_e64 v167, 0, 1.0, vcc
	v_add_u32_e32 v142, 2, v141
	v_cmp_le_u32_e32 vcc, v142, v136
	s_nop 1
	v_cndmask_b32_e64 v168, 0, 1.0, vcc
	v_add_u32_e32 v142, 3, v141
	v_cmp_le_u32_e32 vcc, v142, v136
	s_nop 1
	v_cndmask_b32_e64 v169, 0, 1.0, vcc
	v_readlane_b32 s101, v244, 27
	s_bfe_u32 s101, s101, 0x20003
	v_add_u32_e32 v142, s13, v137
	s_lshl_b32 s14, s101, 8
	v_lshl_add_u32 v143, v136, 4, s14
	s_movk_i32 s15, 0xc00
	v_mad_u32_u24 v118, v142, s15, v143
	s_add_i32 s14, s14, s12
	v_lshl_add_u32 v143, v136, 1, s14
	v_mad_u32_u24 v119, v142, s15, v143
	v_add_u32_e32 v119, 0x800, v119
	v_add_u32_e32 v142, s13, v136
	s_lshl_b32 s15, s101, 2
	v_lshl_add_u32 v140, v142, 5, s15
	v_add_u32_e32 v142, s13, v141
	v_lshl_add_u32 v57, v142, 11, v143
	v_add_u32_e32 v57, 0x400, v57
	v_add_u32_e32 v58, 0x1000, v57
	v_lshlrev_b32_e32 v59, 6, v136
	v_lshl_add_u32 v59, v138, 4, v59
	v_mov_b32_e32 v12, 0
	v_mov_b32_e32 v13, 0
	v_mov_b32_e32 v14, 0
	v_mov_b32_e32 v15, 0
	v_mov_b32_e32 v16, 0
	v_mov_b32_e32 v17, 0
	v_mov_b32_e32 v18, 0
	v_mov_b32_e32 v19, 0
	s_barrier
	global_load_dwordx4 v[108:111], v118, s[4:5]
	global_load_dwordx4 v[112:115], v118, s[4:5] offset:1024
	global_load_ushort v116, v119, s[4:5]
	global_load_dword v117, v140, s[6:7]
	s_add_u32 s4, s4, 0xc000
	s_addc_u32 s5, s5, 0
	s_add_u32 s6, s6, 0x200
	s_addc_u32 s7, s7, 0
	global_load_dwordx4 v[88:91], v59, s[10:11]
	s_add_u32 s10, s10, 0x400
	s_addc_u32 s11, s11, 0
	v_mov_b32_e32 v148, v157
	v_mov_b32_e32 v149, v158
	v_mov_b32_e32 v150, v159
	s_waitcnt vmcnt(0)
	v_lshlrev_b32_e32 v120, 16, v108
	v_and_b32_e32 v121, 0xffff0000, v108
	v_lshlrev_b32_e32 v122, 16, v109
	v_and_b32_e32 v123, 0xffff0000, v109
	v_lshlrev_b32_e32 v124, 16, v110
	v_and_b32_e32 v125, 0xffff0000, v110
	v_lshlrev_b32_e32 v126, 16, v111
	v_and_b32_e32 v127, 0xffff0000, v111
	v_lshlrev_b32_e32 v128, 16, v112
	v_and_b32_e32 v129, 0xffff0000, v112
	v_lshlrev_b32_e32 v130, 16, v113
	v_and_b32_e32 v131, 0xffff0000, v113
	v_lshlrev_b32_e32 v132, 16, v114
	v_and_b32_e32 v133, 0xffff0000, v114
	v_lshlrev_b32_e32 v134, 16, v115
	v_and_b32_e32 v135, 0xffff0000, v115
	v_mov_b32_e32 v136, v117
	v_lshlrev_b32_e32 v137, 16, v116
	ds_write_b128 v148, v[120:123]
	v_add_f32_dpp v136, v136, v136 row_shr:1 row_mask:0xf bank_mask:0xf bound_ctrl:1
	ds_write_b128 v148, v[124:127] offset:16
	ds_write_b128 v148, v[128:131] offset:8192
	v_add_f32_dpp v136, v136, v136 row_shr:2 row_mask:0xf bank_mask:0xf bound_ctrl:1
	ds_write_b128 v148, v[132:135] offset:8208
	ds_write_b32 v149, v137
	v_add_f32_dpp v136, v136, v136 row_shr:4 row_mask:0xf bank_mask:0xf bound_ctrl:1
	s_nop 1
	v_add_f32_dpp v136, v136, v136 row_shr:8 row_mask:0xf bank_mask:0xf bound_ctrl:1
	s_nop 0
	v_max_f32_e32 v136, 0xc2a00000, v136
	v_mul_f32_e32 v136, 0x3fb8aa3b, v136
	v_exp_f32_e32 v138, v136
	v_exp_f32_e64 v139, -v136
	s_nop 0
	v_mul_f32_e32 v136, 0x3db504f3, v138
	ds_write_b32 v150, v139 offset:17408
	ds_write_b32 v150, v138 offset:17536
	ds_write_b32 v150, v136 offset:17472
	global_load_dwordx4 v[108:111], v118, s[4:5]
	global_load_dwordx4 v[112:115], v118, s[4:5] offset:1024
	global_load_ushort v116, v119, s[4:5]
	global_load_dword v117, v140, s[6:7]
	s_add_u32 s4, s4, 0xc000
	s_addc_u32 s5, s5, 0
	s_add_u32 s6, s6, 0x200
	s_addc_u32 s7, s7, 0
	s_mov_b32 s0, 0
	s_mov_b32 s1, 0
	s_waitcnt lgkmcnt(0)
	s_barrier
; __device__ __forceinline__ void gdn_item(const Params& p, int item, float* sm) {
;     ...
;   for (int ch = 0; ch < NCH; ch++) {
;     const int bi = ch & 1;
;     const int t0 = PADR + ch * TC;
;     if (ch + 1 < NCH) GDN_LOAD(t0 + TC)
;     ...
;     if (ch + 1 < NCH) GDN_STORE(bi ^ 1)
.Lgd_chunk:
	v_add_u32_e32 v141, s1, v151
	v_add_u32_e32 v142, s1, v152
	v_add_u32_e32 v143, s1, v153
	v_add_u32_e32 v144, s1, v154
	v_mov_b32_e32 v145, s1
	s_xor_b32 s2, s1, 0x4500
	s_and_b32 s12, s0, 1
	s_mul_i32 s12, s12, 0x3000
	v_add_u32_e32 v146, s12, v155
	v_add_u32_e32 v147, s12, v156
	ds_read_b128 v[20:23], v141 offset:8192
	ds_read_b128 v[28:31], v141 offset:0
	ds_read_b128 v[24:27], v141 offset:8256
	ds_read_b128 v[32:35], v141 offset:64
	v_add_u32_e32 v148, s2, v157
	v_add_u32_e32 v149, s2, v158
	v_add_u32_e32 v150, s2, v159
	s_waitcnt lgkmcnt(0)
	v_mfma_f32_16x16x4_f32 v[60:63], v20, v12, 0
	ds_read_b32 v36, v142 offset:8192
	v_mfma_f32_16x16x4_f32 v[64:67], v28, v12, 0
	ds_read_b32 v37, v142 offset:8704
	v_mfma_f32_16x16x4_f32 v[68:71], v20, v28, 0
	v_mfma_f32_16x16x4_f32 v[60:63], v21, v13, v[60:63]
	ds_read_b32 v38, v142 offset:9216
	v_mfma_f32_16x16x4_f32 v[64:67], v29, v13, v[64:67]
	ds_read_b32 v39, v142 offset:9728
	v_mfma_f32_16x16x4_f32 v[68:71], v21, v29, v[68:71]
	v_mfma_f32_16x16x4_f32 v[60:63], v22, v14, v[60:63]
	ds_read_b32 v40, v142 offset:8256
	v_mfma_f32_16x16x4_f32 v[64:67], v30, v14, v[64:67]
	ds_read_b32 v41, v142 offset:8768
	v_mfma_f32_16x16x4_f32 v[68:71], v22, v30, v[68:71]
	v_mfma_f32_16x16x4_f32 v[60:63], v23, v15, v[60:63]
	ds_read_b32 v42, v142 offset:9280
	v_mfma_f32_16x16x4_f32 v[64:67], v31, v15, v[64:67]
	ds_read_b32 v43, v142 offset:9792
	v_mfma_f32_16x16x4_f32 v[68:71], v23, v31, v[68:71]
	v_mfma_f32_16x16x4_f32 v[60:63], v24, v16, v[60:63]
	ds_read_b128 v[44:47], v143 offset:16384
	v_mfma_f32_16x16x4_f32 v[64:67], v32, v16, v[64:67]
	ds_read_b128 v[48:51], v144 offset:17408
	v_mfma_f32_16x16x4_f32 v[68:71], v24, v32, v[68:71]
	v_mfma_f32_16x16x4_f32 v[60:63], v25, v17, v[60:63]
	ds_read_b128 v[52:55], v144 offset:17472
	v_mfma_f32_16x16x4_f32 v[64:67], v33, v17, v[64:67]
	ds_read_b32 v56, v145 offset:17596
	v_mfma_f32_16x16x4_f32 v[68:71], v25, v33, v[68:71]
	v_mfma_f32_16x16x4_f32 v[60:63], v26, v18, v[60:63]
	v_mfma_f32_16x16x4_f32 v[64:67], v34, v18, v[64:67]
	v_mfma_f32_16x16x4_f32 v[68:71], v26, v34, v[68:71]
	v_mfma_f32_16x16x4_f32 v[60:63], v27, v19, v[60:63]
	v_mfma_f32_16x16x4_f32 v[64:67], v35, v19, v[64:67]
	v_mfma_f32_16x16x4_f32 v[68:71], v27, v35, v[68:71]
	s_cmp_eq_u32 s0, 512
	s_cbranch_scc1 .Lgd_noprep
	s_waitcnt vmcnt(0)
	v_lshlrev_b32_e32 v120, 16, v108
	v_and_b32_e32 v121, 0xffff0000, v108
	v_lshlrev_b32_e32 v122, 16, v109
	v_and_b32_e32 v123, 0xffff0000, v109
	v_lshlrev_b32_e32 v124, 16, v110
	v_and_b32_e32 v125, 0xffff0000, v110
	v_lshlrev_b32_e32 v126, 16, v111
	v_and_b32_e32 v127, 0xffff0000, v111
	v_lshlrev_b32_e32 v128, 16, v112
	v_and_b32_e32 v129, 0xffff0000, v112
	v_lshlrev_b32_e32 v130, 16, v113
	v_and_b32_e32 v131, 0xffff0000, v113
	v_lshlrev_b32_e32 v132, 16, v114
	v_and_b32_e32 v133, 0xffff0000, v114
	v_lshlrev_b32_e32 v134, 16, v115
	v_and_b32_e32 v135, 0xffff0000, v115
	v_mov_b32_e32 v136, v117
	v_lshlrev_b32_e32 v137, 16, v116
	ds_write_b128 v148, v[120:123]
	v_add_f32_dpp v136, v136, v136 row_shr:1 row_mask:0xf bank_mask:0xf bound_ctrl:1
	ds_write_b128 v148, v[124:127] offset:16
	ds_write_b128 v148, v[128:131] offset:8192
	v_add_f32_dpp v136, v136, v136 row_shr:2 row_mask:0xf bank_mask:0xf bound_ctrl:1
	ds_write_b128 v148, v[132:135] offset:8208
	ds_write_b32 v149, v137
	v_add_f32_dpp v136, v136, v136 row_shr:4 row_mask:0xf bank_mask:0xf bound_ctrl:1
	s_nop 1
	v_add_f32_dpp v136, v136, v136 row_shr:8 row_mask:0xf bank_mask:0xf bound_ctrl:1
	s_nop 0
	v_max_f32_e32 v136, 0xc2a00000, v136
	v_mul_f32_e32 v136, 0x3fb8aa3b, v136
	v_exp_f32_e32 v138, v136
	v_exp_f32_e64 v139, -v136
	s_nop 0
	v_mul_f32_e32 v136, 0x3db504f3, v138
	ds_write_b32 v150, v139 offset:17408
	ds_write_b32 v150, v138 offset:17536
	ds_write_b32 v150, v136 offset:17472
	s_cmp_ge_u32 s0, 511
	s_cbranch_scc1 .Lgd_prepd
	global_load_dwordx4 v[108:111], v118, s[4:5]
	global_load_dwordx4 v[112:115], v118, s[4:5] offset:1024
	global_load_ushort v116, v119, s[4:5]
	global_load_dword v117, v140, s[6:7]
	s_add_u32 s4, s4, 0xc000
	s_addc_u32 s5, s5, 0
	s_add_u32 s6, s6, 0x200
	s_addc_u32 s7, s7, 0
	s_branch .Lgd_prepd
; __device__ __forceinline__ void gdn_item(const Params& p, int item, float* sm) {
;     ...
;         const float ks = dpp_sum16(pa + pb2);
;         const float qs = dpp_sum16(qa + qb2);
;         const float coef = be * (v - g * ks);
;         const float oo = g * qs + coef * qk;
;         S[0] = g * S[0] + coef * k0.x; S[1] = g * S[1] + coef * k0.y; S[2] = g * S[2] + coef * k0.z; S[3] = g * S[3] + coef * k0.w;
;         S[4] = g * S[4] + coef * k1.x; S[5] = g * S[5] + coef * k1.y; S[6] = g * S[6] + coef * k1.z; S[7] = g * S[7] + coef * k1.w;
;         oreg[t] = oo * 0.08838834764831845f;
;       }
;       if (sub == 0) {
; #pragma unroll
;         for (int t = 0; t < TC; t++) bo[t * 16 + cw] = oreg[t];
;       }
;     }
;     if (ch + 1 < NCH) GDN_STORE(bi ^ 1)
;     __syncthreads();
;     {
;       const float ov = sm[bi * BUF + 2 * TC * 128 + TC * 16 + 2 * TC + ltt * 16 + lseg];
;       O[(rowb + t0 + ltt) * D + 512 + h * 128 + c0 + lseg] = f2bf(ov);
.Lgd_noprep:
	s_waitcnt vmcnt(0)
	s_nop 7
	s_nop 3
.Lgd_prepd:
	ds_write_b128 v146, v[60:63]
	ds_write_b128 v146, v[64:67] offset:1024
	ds_write_b128 v146, v[68:71] offset:2048
	s_waitcnt lgkmcnt(0)
	s_barrier
	ds_read_b128 v[72:75], v147 offset:0
	ds_read_b128 v[76:79], v147 offset:3072
	ds_read_b128 v[80:83], v147 offset:6144
	ds_read_b128 v[84:87], v147 offset:9216
	s_waitcnt lgkmcnt(0)
	v_add_f32_e32 v72, v72, v76
	v_add_f32_e32 v80, v80, v84
	v_add_f32_e32 v73, v73, v77
	v_add_f32_e32 v81, v81, v85
	v_add_f32_e32 v74, v74, v78
	v_add_f32_e32 v82, v82, v86
	v_add_f32_e32 v75, v75, v79
	v_add_f32_e32 v83, v83, v87
	v_add_f32_e32 v72, v72, v80
	v_add_f32_e32 v73, v73, v81
	v_add_f32_e32 v74, v74, v82
	v_add_f32_e32 v75, v75, v83
	v_fma_f32 v96, v44, v48, -v72
	v_fma_f32 v97, v45, v49, -v73
	v_fma_f32 v98, v46, v50, -v74
	v_fma_f32 v99, v47, v51, -v75
	s_nop 1
	v_mfma_f32_16x16x4_f32 v[100:103], v88, v96, 0
	v_mfma_f32_16x16x4_f32 v[100:103], v89, v97, v[100:103]
	v_mfma_f32_16x16x4_f32 v[100:103], v90, v98, v[100:103]
	v_mfma_f32_16x16x4_f32 v[100:103], v91, v99, v[100:103]
	s_cmp_eq_u32 s0, 512
	s_cbranch_scc1 .Lgd_nomv
	global_load_dwordx4 v[88:91], v59, s[10:11]
	s_add_u32 s10, s10, 0x400
	s_addc_u32 s11, s11, 0
.Lgd_nomv:
	s_and_b32 s12, s0, 3
	s_cmp_eq_u32 s12, s100
	s_cbranch_scc0 .Lgd_upd
	ds_read_b128 v[72:75], v147 offset:1024
	ds_read_b128 v[76:79], v147 offset:4096
	ds_read_b128 v[80:83], v147 offset:7168
	ds_read_b128 v[84:87], v147 offset:10240
	s_waitcnt lgkmcnt(0)
	v_add_f32_e32 v72, v72, v76
	v_add_f32_e32 v80, v80, v84
	v_add_f32_e32 v73, v73, v77
	v_add_f32_e32 v81, v81, v85
	v_add_f32_e32 v74, v74, v78
	v_add_f32_e32 v82, v82, v86
	v_add_f32_e32 v75, v75, v79
	v_add_f32_e32 v83, v83, v87
	v_add_f32_e32 v104, v72, v80
	v_add_f32_e32 v105, v73, v81
	v_add_f32_e32 v106, v74, v82
	v_add_f32_e32 v107, v75, v83
	ds_read_b128 v[72:75], v147 offset:2048
	ds_read_b128 v[76:79], v147 offset:5120
	ds_read_b128 v[80:83], v147 offset:8192
	ds_read_b128 v[84:87], v147 offset:11264
	s_waitcnt lgkmcnt(0)
	v_add_f32_e32 v72, v72, v76
	v_add_f32_e32 v80, v80, v84
	v_add_f32_e32 v73, v73, v77
	v_add_f32_e32 v81, v81, v85
	v_add_f32_e32 v74, v74, v78
	v_add_f32_e32 v82, v82, v86
	v_add_f32_e32 v75, v75, v79
	v_add_f32_e32 v83, v83, v87
	v_add_f32_e32 v72, v72, v80
	v_add_f32_e32 v73, v73, v81
	v_add_f32_e32 v74, v74, v82
	v_add_f32_e32 v75, v75, v83
	v_mul_f32_e32 v72, v72, v166
	v_mul_f32_e32 v73, v73, v167
	v_mul_f32_e32 v74, v74, v168
	v_mul_f32_e32 v75, v75, v169
	s_nop 7
	s_nop 1
	v_mfma_f32_16x16x4_f32 v[104:107], v72, v100, v[104:107]
	v_mfma_f32_16x16x4_f32 v[104:107], v73, v101, v[104:107]
	v_mfma_f32_16x16x4_f32 v[104:107], v74, v102, v[104:107]
	v_mfma_f32_16x16x4_f32 v[104:107], v75, v103, v[104:107]
.Lgd_upd:
	s_nop 5
	v_mfma_f32_16x16x4_f32 v[12:15], v36, v100, v[12:15]
	v_mfma_f32_16x16x4_f32 v[16:19], v40, v100, v[16:19]
	v_mfma_f32_16x16x4_f32 v[12:15], v37, v101, v[12:15]
	v_mfma_f32_16x16x4_f32 v[16:19], v41, v101, v[16:19]
	v_mfma_f32_16x16x4_f32 v[12:15], v38, v102, v[12:15]
	v_mfma_f32_16x16x4_f32 v[16:19], v42, v102, v[16:19]
	v_mfma_f32_16x16x4_f32 v[12:15], v39, v103, v[12:15]
	v_mfma_f32_16x16x4_f32 v[16:19], v43, v103, v[16:19]
	s_cmp_eq_u32 s12, s100
	s_cbranch_scc0 .Lgd_noout
	s_nop 7
	s_nop 3
	v_mul_f32_e32 v104, v104, v52
	v_mul_f32_e32 v105, v105, v53
	v_mul_f32_e32 v106, v106, v54
	v_mul_f32_e32 v107, v107, v55
	v_cvt_pk_bf16_f32 v104, v104, v104
	v_cvt_pk_bf16_f32 v105, v105, v105
	v_cvt_pk_bf16_f32 v106, v106, v106
	v_cvt_pk_bf16_f32 v107, v107, v107
	global_store_short v57, v104, s[8:9]
	global_store_short v57, v105, s[8:9] offset:2048
	global_store_short v58, v106, s[8:9]
	global_store_short v58, v107, s[8:9] offset:2048
.Lgd_noout:
	s_add_u32 s8, s8, 0x8000
	s_addc_u32 s9, s9, 0
	s_nop 6
	v_mul_f32_e32 v12, v12, v56
	v_mul_f32_e32 v13, v13, v56
	v_mul_f32_e32 v14, v14, v56
	v_mul_f32_e32 v15, v15, v56
	v_mul_f32_e32 v16, v16, v56
	v_mul_f32_e32 v17, v17, v56
	v_mul_f32_e32 v18, v18, v56
	v_mul_f32_e32 v19, v19, v56
	s_mov_b32 s1, s2
	s_add_i32 s0, s0, 1
	s_cmp_lg_u32 s0, 513
	s_cbranch_scc1 .Lgd_chunk
	s_waitcnt lgkmcnt(0)
	s_setprio 0
